# e21: row-sum slots carry a sign-bit written flag (zeroed in P2), panel counters bumped without waiting for store acks and used as a hint only; stage-0 counter polled behind the last x load
# speedup vs baseline: 1.0070x; 1.0070x over previous
; #define SUB(i, ...) do { if (PROBE_PH == phk && PROBE_SUB == (i)) { __syncthreads(); tp0 = __builtin_amdgcn_s_memrealtime(); } __VA_ARGS__ if (PROBE_PH == phk && PROBE_SUB == (i)) { asm volatile("s_waitcnt vmcnt(0)" ::: "memory"); __syncthreads(); tp1 = __builtin_amdgcn_s_memrealtime(); } } while (0)
; __global__ void __launch_bounds__(NTHREADS, 2) mk_fwd(Args a) {
;     ...
;     PHASE(2,
;         pg8::DenseOrder S; S.init(M_LAT / 256, 12, G, bx, WGM_IN);
;         EpiInProj E{(f16*)(a.ws + WS_UPOOL), (f16*)(a.ws + WS_X), (f16*)(a.ws + WS_ZS)};
;         SUB(0, pg8::gemm_phase<CfgDense2048, EpiInProj, pg8::DenseOrder, true, true>(lds, (const char*)(a.ws + WS_H), (const char*)(a.ws + WS_WIN), S, E); );
.LBB0_284:
	s_mov_b32 s98, 0
	s_cmp_lt_i32 s78, 3
	s_cselect_b64 s[0:1], -1, 0
	s_and_b64 s[6:7], s[0:1], s[2:3]
	s_andn2_b64 vcc, exec, s[6:7]
	s_cbranch_vccnz .LBB0_436
	v_lshlrev_b32_e32 v255, 4, v0
	s_lshl_b32 s99, s16, 13
	s_add_u32 s99, s99, 0x200000
	v_add_u32_e32 v255, s99, v255
	v_mov_b32_e32 v250, 0
	v_mov_b32_e32 v251, 0
	v_mov_b32_e32 v252, 0
	v_mov_b32_e32 v253, 0
	global_store_dwordx4 v255, v[250:253], s[50:51]
	s_bitcmp1_b32 s16, 3
	s_cbranch_scc0 .Lp2_gemm
	s_mov_b32 s98, 1
	v_lshrrev_b32_e32 v1, 3, v0
	v_and_b32_e32 v130, 15, v0
	v_lshrrev_b32_e32 v131, 2, v0
	s_add_u32 s8, s50, 0xc300000
	s_addc_u32 s9, s51, 0
	s_branch .LBB0_431

;     __device__ __forceinline__ void operator()(AccRef acc, const Unit& u, int wr, int wc, int fr, int fq) const {
;         int row0 = u.pm * 256 + wr * 64 + fr; asm volatile("" : "+v"(row0)); int col0 = u.pn * 256 + wc * 32 + 8 * fq; asm volatile("" : "+v"(col0));
;         const float* gate = mod + (size_t)(u.pm >= 32 ? 1 : 0) * 3 * D + 2 * D + col0;
;         f32x4 gv[2][2];
; #pragma unroll
;         for (int bj = 0; bj < 2; ++bj)
; #pragma unroll
;             for (int n = 0; n < 2; ++n) gv[bj][n] = *(const f32x4*)(gate + bj * HALF + n * 4);
; #pragma unroll
;         for (int ai = 0; ai < 2; ++ai)
; #pragma unroll
;             for (int mp = 0; mp < 2; ++mp) { f32x4 xv[2][2][2];
; #pragma unroll
;                 for (int mm = 0; mm < 2; ++mm)
; #pragma unroll
;                     for (int bj = 0; bj < 2; ++bj)
; #pragma unroll
;                         for (int n = 0; n < 2; ++n) xv[mm][bj][n] = ld_nt(x + (size_t)(row0 + ai * HALF + (mp * 2 + mm) * 16) * D + col0 + bj * HALF + n * 4);
;                 __builtin_amdgcn_sched_barrier(0);
; #pragma unroll
;                 for (int mm = 0; mm < 2; ++mm) { const int m = mp * 2 + mm; const int row = row0 + ai * HALF + m * 16; const size_t o = (size_t)row * D + col0; float ss = 0.f;
; #pragma unroll
;                     for (int bj = 0; bj < 2; ++bj) { const f32x4 r0 = xv[mm][bj][0] + gv[bj][0] * acc[ai][bj][m][0], r1 = xv[mm][bj][1] + gv[bj][1] * acc[ai][bj][m][1];
;                         *(u32x4*)(xo + o + bj * HALF) = pack8h(r0, r1);
;                         ss += ((r0[0] * r0[0] + r0[1] * r0[1]) + (r0[2] * r0[2] + r0[3] * r0[3])) + ((r1[0] * r1[0] + r1[1] * r1[1]) + (r1[2] * r1[2] + r1[3] * r1[3])); }
;                     ss += __shfl_xor(ss, 16); ss += __shfl_xor(ss, 32);
;                     if (fq == 0) rowss[(size_t)row * 32 + u.pn * 4 + wc] = ss; } }
; __device__ __forceinline__ void final_rows(int gw, int lane, const f16* xo, float* out, const float* fg, const float* rowss) {
;     ...
;         for (int rr = 0; rr < 4; ++rr) { part[rr] = lane < 32 ? rowss[(size_t)(r0 + rr) * 32 + lane] : 0.f;
; #pragma unroll
;             for (int j = 0; j < 4; ++j) v[rr][j] = *(const u32x4*)(xo + (size_t)(r0 + rr) * D + 512 * j + 8 * lane); }
;         __builtin_amdgcn_sched_barrier(0);
; #pragma unroll
.LBB0_1154:
	v_lshl_add_u32 v172, s58, 8, v178
	v_lshl_or_b32 v170, s22, 8, v180
	v_readlane_b32 s80, v254, 2
	v_readlane_b32 s81, v254, 3
	v_lshlrev_b32_e32 v173, 13, v172
	v_lshlrev_b32_e32 v187, 7, v172
	v_lshlrev_b32_e32 v171, 2, v170
	v_lshl_add_u32 v173, v170, 2, v173
	s_lshl_b32 s18, s22, 2
	s_add_u32 s18, s18, s72
	s_lshl_b32 s18, s18, 2
	s_add_u32 s88, s26, s18
	s_addc_u32 s89, s27, 0
	v_xor_b32_e32 v186, 16, v184
	v_xor_b32_e32 v185, 32, v184
	v_lshrrev_b32_e32 v174, 4, v184
	v_lshlrev_b32_e32 v186, 2, v186
	v_lshlrev_b32_e32 v185, 2, v185
	v_lshl_add_u32 v174, v174, 5, v187
	s_mov_b32 s94, 0xba000000
	s_mov_b32 s95, 0x358637bd
	s_mov_b64 s[82:83], s[48:49]
	s_lshr_b32 s59, s65, 10
	global_load_dwordx4 v[144:147], v171, s[46:47]
	global_load_dwordx4 v[148:151], v171, s[46:47] offset:16
	global_load_dwordx4 v[152:155], v171, s[46:47] offset:512
	global_load_dwordx4 v[156:159], v171, s[46:47] offset:528
	s_add_u32 s84, s80, 0x20000
	s_addc_u32 s85, s81, 0
	global_load_dwordx4 v[188:191], v173, s[84:85] nt
	global_load_dwordx4 v[192:195], v173, s[84:85] offset:16 nt
	global_load_dwordx4 v[196:199], v173, s[84:85] offset:512 nt
	global_load_dwordx4 v[200:203], v173, s[84:85] offset:528 nt
	s_add_u32 s84, s80, 0x40000
	s_addc_u32 s85, s81, 0
	global_load_dwordx4 v[104:107], v173, s[84:85] nt
	global_load_dwordx4 v[108:111], v173, s[84:85] offset:16 nt
	global_load_dwordx4 v[112:115], v173, s[84:85] offset:512 nt
	global_load_dwordx4 v[120:123], v173, s[84:85] offset:528 nt
	s_waitcnt vmcnt(12)
	v_pk_fma_f32 v[140:141], v[140:141], v[218:219], v[234:235]
	v_pk_fma_f32 v[142:143], v[142:143], v[220:221], v[236:237]
	v_pk_fma_f32 v[136:137], v[136:137], v[222:223], v[238:239]
	v_pk_fma_f32 v[138:139], v[138:139], v[224:225], v[240:241]
	v_pk_fma_f32 v[132:133], v[132:133], v[226:227], v[242:243]
	v_pk_fma_f32 v[134:135], v[134:135], v[228:229], v[244:245]
	v_pk_fma_f32 v[128:129], v[128:129], v[230:231], v[246:247]
	v_pk_fma_f32 v[130:131], v[130:131], v[232:233], v[248:249]
	s_add_u32 s84, s80, 0x60000
	s_addc_u32 s85, s81, 0
	global_load_dwordx4 v[234:237], v173, s[84:85] nt
	global_load_dwordx4 v[238:241], v173, s[84:85] offset:16 nt
	global_load_dwordx4 v[242:245], v173, s[84:85] offset:512 nt
	global_load_dwordx4 v[246:249], v173, s[84:85] offset:528 nt
	v_pk_mul_f32 v[176:177], v[140:141], v[140:141]
	v_pk_fma_f32 v[176:177], v[142:143], v[142:143], v[176:177]
	v_pk_fma_f32 v[176:177], v[136:137], v[136:137], v[176:177]
	v_pk_fma_f32 v[176:177], v[138:139], v[138:139], v[176:177]
	v_pk_fma_f32 v[176:177], v[132:133], v[132:133], v[176:177]
	v_pk_fma_f32 v[176:177], v[134:135], v[134:135], v[176:177]
	v_pk_fma_f32 v[176:177], v[128:129], v[128:129], v[176:177]
	v_pk_fma_f32 v[176:177], v[130:131], v[130:131], v[176:177]
	v_add_f32_e32 v204, v176, v177
	s_waitcnt vmcnt(8)
	v_pk_fma_f32 v[124:125], v[124:125], v[218:219], v[188:189]
	v_pk_fma_f32 v[126:127], v[126:127], v[220:221], v[190:191]
	v_pk_fma_f32 v[116:117], v[116:117], v[222:223], v[192:193]
	v_pk_fma_f32 v[118:119], v[118:119], v[224:225], v[194:195]
	v_pk_fma_f32 v[100:101], v[100:101], v[226:227], v[196:197]
	v_pk_fma_f32 v[102:103], v[102:103], v[228:229], v[198:199]
	v_pk_fma_f32 v[96:97], v[96:97], v[230:231], v[200:201]
	v_pk_fma_f32 v[98:99], v[98:99], v[232:233], v[202:203]
	s_add_u32 s84, s80, 0x100000
	s_addc_u32 s85, s81, 0
	global_load_dwordx4 v[188:191], v173, s[84:85] nt
	global_load_dwordx4 v[192:195], v173, s[84:85] offset:16 nt
	global_load_dwordx4 v[196:199], v173, s[84:85] offset:512 nt
	global_load_dwordx4 v[200:203], v173, s[84:85] offset:528 nt
	v_pk_mul_f32 v[176:177], v[124:125], v[124:125]
	v_pk_fma_f32 v[176:177], v[126:127], v[126:127], v[176:177]
	v_pk_fma_f32 v[176:177], v[116:117], v[116:117], v[176:177]
	v_pk_fma_f32 v[176:177], v[118:119], v[118:119], v[176:177]
	v_pk_fma_f32 v[176:177], v[100:101], v[100:101], v[176:177]
	v_pk_fma_f32 v[176:177], v[102:103], v[102:103], v[176:177]
	v_pk_fma_f32 v[176:177], v[96:97], v[96:97], v[176:177]
	v_pk_fma_f32 v[176:177], v[98:99], v[98:99], v[176:177]
	v_add_f32_e32 v205, v176, v177
	s_waitcnt vmcnt(8)
	v_pk_fma_f32 v[92:93], v[92:93], v[218:219], v[104:105]
	v_pk_fma_f32 v[94:95], v[94:95], v[220:221], v[106:107]
	v_pk_fma_f32 v[88:89], v[88:89], v[222:223], v[108:109]
	v_pk_fma_f32 v[90:91], v[90:91], v[224:225], v[110:111]
	v_pk_fma_f32 v[84:85], v[84:85], v[226:227], v[112:113]
	v_pk_fma_f32 v[86:87], v[86:87], v[228:229], v[114:115]
	v_pk_fma_f32 v[80:81], v[80:81], v[230:231], v[120:121]
	v_pk_fma_f32 v[82:83], v[82:83], v[232:233], v[122:123]
	s_add_u32 s84, s80, 0x120000
	s_addc_u32 s85, s81, 0
	global_load_dwordx4 v[104:107], v173, s[84:85] nt
	global_load_dwordx4 v[108:111], v173, s[84:85] offset:16 nt
	global_load_dwordx4 v[112:115], v173, s[84:85] offset:512 nt
	global_load_dwordx4 v[120:123], v173, s[84:85] offset:528 nt
	v_pk_mul_f32 v[176:177], v[92:93], v[92:93]
	v_pk_fma_f32 v[176:177], v[94:95], v[94:95], v[176:177]
	v_pk_fma_f32 v[176:177], v[88:89], v[88:89], v[176:177]
	v_pk_fma_f32 v[176:177], v[90:91], v[90:91], v[176:177]
	v_pk_fma_f32 v[176:177], v[84:85], v[84:85], v[176:177]
	v_pk_fma_f32 v[176:177], v[86:87], v[86:87], v[176:177]
	v_pk_fma_f32 v[176:177], v[80:81], v[80:81], v[176:177]
	v_pk_fma_f32 v[176:177], v[82:83], v[82:83], v[176:177]
	v_add_f32_e32 v206, v176, v177
	s_waitcnt vmcnt(8)
; __device__ __forceinline__ u32x4 pack8h(const f32x4 v0, const f32x4 v1) { u32x4 w; w.x = pk_h16(v0[0], v0[1]); w.y = pk_h16(v0[2], v0[3]); w.z = pk_h16(v1[0], v1[1]); w.w = pk_h16(v1[2], v1[3]); return w; }
;     __device__ __forceinline__ void operator()(AccRef acc, const Unit& u, int wr, int wc, int fr, int fq) const {
;     ...
;                 for (int mm = 0; mm < 2; ++mm) { const int m = mp * 2 + mm; const int row = row0 + ai * HALF + m * 16; const size_t o = (size_t)row * D + col0; float ss = 0.f;
; #pragma unroll
;                     for (int bj = 0; bj < 2; ++bj) { const f32x4 r0 = xv[mm][bj][0] + gv[bj][0] * acc[ai][bj][m][0], r1 = xv[mm][bj][1] + gv[bj][1] * acc[ai][bj][m][1];
;                         *(u32x4*)(xo + o + bj * HALF) = pack8h(r0, r1);
;                         ss += ((r0[0] * r0[0] + r0[1] * r0[1]) + (r0[2] * r0[2] + r0[3] * r0[3])) + ((r1[0] * r1[0] + r1[1] * r1[1]) + (r1[2] * r1[2] + r1[3] * r1[3])); }
;                     ss += __shfl_xor(ss, 16); ss += __shfl_xor(ss, 32);
;                     if (fq == 0) rowss[(size_t)row * 32 + u.pn * 4 + wc] = ss; } }
	v_pk_fma_f32 v[76:77], v[76:77], v[218:219], v[234:235]
	v_pk_fma_f32 v[78:79], v[78:79], v[220:221], v[236:237]
	v_pk_fma_f32 v[72:73], v[72:73], v[222:223], v[238:239]
	v_pk_fma_f32 v[74:75], v[74:75], v[224:225], v[240:241]
	v_pk_fma_f32 v[68:69], v[68:69], v[226:227], v[242:243]
	v_pk_fma_f32 v[70:71], v[70:71], v[228:229], v[244:245]
	v_pk_fma_f32 v[64:65], v[64:65], v[230:231], v[246:247]
	v_pk_fma_f32 v[66:67], v[66:67], v[232:233], v[248:249]
	s_add_u32 s84, s80, 0x140000
	s_addc_u32 s85, s81, 0
	global_load_dwordx4 v[234:237], v173, s[84:85] nt
	global_load_dwordx4 v[238:241], v173, s[84:85] offset:16 nt
	global_load_dwordx4 v[242:245], v173, s[84:85] offset:512 nt
	global_load_dwordx4 v[246:249], v173, s[84:85] offset:528 nt
	v_pk_mul_f32 v[176:177], v[76:77], v[76:77]
	v_pk_fma_f32 v[176:177], v[78:79], v[78:79], v[176:177]
	v_pk_fma_f32 v[176:177], v[72:73], v[72:73], v[176:177]
	v_pk_fma_f32 v[176:177], v[74:75], v[74:75], v[176:177]
	v_pk_fma_f32 v[176:177], v[68:69], v[68:69], v[176:177]
	v_pk_fma_f32 v[176:177], v[70:71], v[70:71], v[176:177]
	v_pk_fma_f32 v[176:177], v[64:65], v[64:65], v[176:177]
	v_pk_fma_f32 v[176:177], v[66:67], v[66:67], v[176:177]
	v_add_f32_e32 v207, v176, v177
	ds_bpermute_b32 v214, v186, v204
	ds_bpermute_b32 v215, v186, v205
	ds_bpermute_b32 v216, v186, v206
	ds_bpermute_b32 v217, v186, v207
	s_waitcnt lgkmcnt(0)
	v_add_f32_e32 v204, v204, v214
	v_add_f32_e32 v205, v205, v215
	v_add_f32_e32 v206, v206, v216
	v_add_f32_e32 v207, v207, v217
	ds_bpermute_b32 v214, v185, v204
	ds_bpermute_b32 v215, v185, v205
	ds_bpermute_b32 v216, v185, v206
	ds_bpermute_b32 v217, v185, v207
	s_waitcnt lgkmcnt(0)
	v_add_f32_e32 v204, v204, v214
	v_add_f32_e32 v205, v205, v215
	v_add_f32_e32 v206, v206, v216
	v_add_f32_e32 v207, v207, v217
	v_or_b32_e32 v204, 0x80000000, v204
	v_or_b32_e32 v205, 0x80000000, v205
	v_or_b32_e32 v206, 0x80000000, v206
	v_or_b32_e32 v207, 0x80000000, v207
	s_and_saveexec_b64 s[20:21], s[2:3]
	s_mov_b64 s[90:91], s[88:89]
	global_store_dword v187, v204, s[90:91] sc0 sc1
	s_add_u32 s90, s88, 0x800
	s_addc_u32 s91, s89, 0
	global_store_dword v187, v205, s[90:91] sc0 sc1
	s_add_u32 s90, s88, 0x1000
	s_addc_u32 s91, s89, 0
	global_store_dword v187, v206, s[90:91] sc0 sc1
	s_add_u32 s90, s88, 0x1800
	s_addc_u32 s91, s89, 0
	global_store_dword v187, v207, s[90:91] sc0 sc1
	s_or_b64 exec, exec, s[20:21]
	s_barrier
	s_cmp_lg_u32 s59, 0
	s_cbranch_scc1 .Lepi_a1
	s_lshl_b32 s18, s58, 6
	s_add_u32 s18, s18, 0xc000
	s_mov_b64 exec, 1
	v_mov_b32_e32 v175, s18
	v_mov_b32_e32 v255, 1
	global_atomic_add v175, v255, s[50:51]
	s_mov_b64 exec, -1
.Lepi_a1:
	s_waitcnt vmcnt(12)
	v_pk_fma_f32 v[60:61], v[60:61], v[218:219], v[188:189]
	v_pk_fma_f32 v[62:63], v[62:63], v[220:221], v[190:191]
	v_pk_fma_f32 v[56:57], v[56:57], v[222:223], v[192:193]
	v_pk_fma_f32 v[58:59], v[58:59], v[224:225], v[194:195]
	v_pk_fma_f32 v[52:53], v[52:53], v[226:227], v[196:197]
	v_pk_fma_f32 v[54:55], v[54:55], v[228:229], v[198:199]
	v_pk_fma_f32 v[48:49], v[48:49], v[230:231], v[200:201]
	v_pk_fma_f32 v[50:51], v[50:51], v[232:233], v[202:203]
	s_add_u32 s84, s80, 0x160000
	s_addc_u32 s85, s81, 0
	global_load_dwordx4 v[188:191], v173, s[84:85] nt
	global_load_dwordx4 v[192:195], v173, s[84:85] offset:16 nt
	global_load_dwordx4 v[196:199], v173, s[84:85] offset:512 nt
	global_load_dwordx4 v[200:203], v173, s[84:85] offset:528 nt
	v_pk_mul_f32 v[176:177], v[60:61], v[60:61]
	v_pk_fma_f32 v[176:177], v[62:63], v[62:63], v[176:177]
	v_pk_fma_f32 v[176:177], v[56:57], v[56:57], v[176:177]
	v_pk_fma_f32 v[176:177], v[58:59], v[58:59], v[176:177]
	v_pk_fma_f32 v[176:177], v[52:53], v[52:53], v[176:177]
	v_pk_fma_f32 v[176:177], v[54:55], v[54:55], v[176:177]
	v_pk_fma_f32 v[176:177], v[48:49], v[48:49], v[176:177]
	v_pk_fma_f32 v[176:177], v[50:51], v[50:51], v[176:177]
	v_add_f32_e32 v208, v176, v177
	s_waitcnt vmcnt(12)
	v_pk_fma_f32 v[44:45], v[44:45], v[218:219], v[104:105]
	v_pk_fma_f32 v[46:47], v[46:47], v[220:221], v[106:107]
	v_pk_fma_f32 v[40:41], v[40:41], v[222:223], v[108:109]
	v_pk_fma_f32 v[42:43], v[42:43], v[224:225], v[110:111]
	v_pk_fma_f32 v[36:37], v[36:37], v[226:227], v[112:113]
	v_pk_fma_f32 v[38:39], v[38:39], v[228:229], v[114:115]
	v_pk_fma_f32 v[32:33], v[32:33], v[230:231], v[120:121]
	v_pk_fma_f32 v[34:35], v[34:35], v[232:233], v[122:123]
	v_pk_mul_f32 v[176:177], v[44:45], v[44:45]
	v_pk_fma_f32 v[176:177], v[46:47], v[46:47], v[176:177]
	v_pk_fma_f32 v[176:177], v[40:41], v[40:41], v[176:177]
	v_pk_fma_f32 v[176:177], v[42:43], v[42:43], v[176:177]
	v_pk_fma_f32 v[176:177], v[36:37], v[36:37], v[176:177]
	v_pk_fma_f32 v[176:177], v[38:39], v[38:39], v[176:177]
	v_pk_fma_f32 v[176:177], v[32:33], v[32:33], v[176:177]
	v_pk_fma_f32 v[176:177], v[34:35], v[34:35], v[176:177]
	v_add_f32_e32 v209, v176, v177
	s_waitcnt vmcnt(8)
	v_pk_fma_f32 v[28:29], v[28:29], v[218:219], v[234:235]
	v_pk_fma_f32 v[30:31], v[30:31], v[220:221], v[236:237]
	v_pk_fma_f32 v[24:25], v[24:25], v[222:223], v[238:239]
	v_pk_fma_f32 v[26:27], v[26:27], v[224:225], v[240:241]
	v_pk_fma_f32 v[20:21], v[20:21], v[226:227], v[242:243]
	v_pk_fma_f32 v[22:23], v[22:23], v[228:229], v[244:245]
	v_pk_fma_f32 v[16:17], v[16:17], v[230:231], v[246:247]
	v_pk_fma_f32 v[18:19], v[18:19], v[232:233], v[248:249]
	v_pk_mul_f32 v[176:177], v[28:29], v[28:29]
	v_pk_fma_f32 v[176:177], v[30:31], v[30:31], v[176:177]
	v_pk_fma_f32 v[176:177], v[24:25], v[24:25], v[176:177]
	v_pk_fma_f32 v[176:177], v[26:27], v[26:27], v[176:177]
	v_pk_fma_f32 v[176:177], v[20:21], v[20:21], v[176:177]
	v_pk_fma_f32 v[176:177], v[22:23], v[22:23], v[176:177]
	v_pk_fma_f32 v[176:177], v[16:17], v[16:17], v[176:177]
	v_pk_fma_f32 v[176:177], v[18:19], v[18:19], v[176:177]
	v_add_f32_e32 v210, v176, v177
	s_cmp_lg_u32 s59, 0
	s_cbranch_scc1 .Lepi_q1
	s_lshl_b32 s18, s58, 6
	s_add_u32 s18, s18, 0xc000
	s_mov_b64 exec, 1
	v_mov_b32_e32 v175, s18
	global_load_dword v255, v175, s[50:51] sc1
	s_mov_b64 exec, -1
.Lepi_q1:
	s_waitcnt vmcnt(0)
	s_cmp_lg_u32 s59, 0
	s_cbranch_scc1 .Lepi_p1
	v_readfirstlane_b32 s19, v255
	s_cmp_lt_u32 s19, 8
	s_cbranch_scc0 .Lepi_p0
	s_lshl_b32 s18, s58, 6
	s_add_u32 s18, s18, 0xc000
	s_mov_b64 exec, 1
	v_mov_b32_e32 v175, s18
	s_mov_b32 vcc_lo, 0

; __device__ __forceinline__ u32x4 pack8h(const f32x4 v0, const f32x4 v1) { u32x4 w; w.x = pk_h16(v0[0], v0[1]); w.y = pk_h16(v0[2], v0[3]); w.z = pk_h16(v1[0], v1[1]); w.w = pk_h16(v1[2], v1[3]); return w; }
;     __device__ __forceinline__ void operator()(AccRef acc, const Unit& u, int wr, int wc, int fr, int fq) const {
;     ...
;                 for (int mm = 0; mm < 2; ++mm) { const int m = mp * 2 + mm; const int row = row0 + ai * HALF + m * 16; const size_t o = (size_t)row * D + col0; float ss = 0.f;
; #pragma unroll
;                     for (int bj = 0; bj < 2; ++bj) { const f32x4 r0 = xv[mm][bj][0] + gv[bj][0] * acc[ai][bj][m][0], r1 = xv[mm][bj][1] + gv[bj][1] * acc[ai][bj][m][1];
;                         *(u32x4*)(xo + o + bj * HALF) = pack8h(r0, r1);
;                         ss += ((r0[0] * r0[0] + r0[1] * r0[1]) + (r0[2] * r0[2] + r0[3] * r0[3])) + ((r1[0] * r1[0] + r1[1] * r1[1]) + (r1[2] * r1[2] + r1[3] * r1[3])); }
;                     ss += __shfl_xor(ss, 16); ss += __shfl_xor(ss, 32);
;                     if (fq == 0) rowss[(size_t)row * 32 + u.pn * 4 + wc] = ss; } }
; __device__ __forceinline__ void final_rows(int gw, int lane, const f16* xo, float* out, const float* fg, const float* rowss) {
;     ...
;         for (int rr = 0; rr < 4; ++rr) { part[rr] = lane < 32 ? rowss[(size_t)(r0 + rr) * 32 + lane] : 0.f;
; #pragma unroll
;             for (int j = 0; j < 4; ++j) v[rr][j] = *(const u32x4*)(xo + (size_t)(r0 + rr) * D + 512 * j + 8 * lane); }
;         __builtin_amdgcn_sched_barrier(0);
; #pragma unroll
;         for (int rr = 0; rr < 4; ++rr) { const float rstd = rsqrtf(wave_sum(part[rr]) * (1.f / D) + EPS); float* rp = out + (size_t)(r0 + rr) * D + 8 * lane;
.Lepi_p1:
	v_pk_fma_f32 v[12:13], v[12:13], v[218:219], v[188:189]
	v_pk_fma_f32 v[14:15], v[14:15], v[220:221], v[190:191]
	v_pk_fma_f32 v[8:9], v[8:9], v[222:223], v[192:193]
	v_pk_fma_f32 v[10:11], v[10:11], v[224:225], v[194:195]
	v_pk_fma_f32 v[4:5], v[4:5], v[226:227], v[196:197]
	v_pk_fma_f32 v[6:7], v[6:7], v[228:229], v[198:199]
	v_pk_fma_f32 v[0:1], v[0:1], v[230:231], v[200:201]
	v_pk_fma_f32 v[2:3], v[2:3], v[232:233], v[202:203]
	v_pk_mul_f32 v[176:177], v[12:13], v[12:13]
	v_pk_fma_f32 v[176:177], v[14:15], v[14:15], v[176:177]
	v_pk_fma_f32 v[176:177], v[8:9], v[8:9], v[176:177]
	v_pk_fma_f32 v[176:177], v[10:11], v[10:11], v[176:177]
	v_pk_fma_f32 v[176:177], v[4:5], v[4:5], v[176:177]
	v_pk_fma_f32 v[176:177], v[6:7], v[6:7], v[176:177]
	v_pk_fma_f32 v[176:177], v[0:1], v[0:1], v[176:177]
	v_pk_fma_f32 v[176:177], v[2:3], v[2:3], v[176:177]
	v_add_f32_e32 v211, v176, v177
	s_mov_b32 s93, 0
	s_barrier
	s_mov_b64 s[90:91], s[26:27]
	global_load_dwordx4 v[188:191], v174, s[90:91]
	global_load_dwordx4 v[192:195], v174, s[90:91] offset:16
	s_add_u32 s90, s26, 0x800
	s_addc_u32 s91, s27, 0
	global_load_dwordx4 v[196:199], v174, s[90:91]
	global_load_dwordx4 v[200:203], v174, s[90:91] offset:16
	s_add_u32 s90, s26, 0x1000
	s_addc_u32 s91, s27, 0
	global_load_dwordx4 v[104:107], v174, s[90:91]
	global_load_dwordx4 v[108:111], v174, s[90:91] offset:16
	s_add_u32 s90, s26, 0x1800
	s_addc_u32 s91, s27, 0
	global_load_dwordx4 v[112:115], v174, s[90:91]
	global_load_dwordx4 v[120:123], v174, s[90:91] offset:16
	ds_bpermute_b32 v214, v186, v208
	ds_bpermute_b32 v215, v186, v209
	ds_bpermute_b32 v216, v186, v210
	ds_bpermute_b32 v217, v186, v211
	s_waitcnt lgkmcnt(0)
	v_add_f32_e32 v208, v208, v214
	v_add_f32_e32 v209, v209, v215
	v_add_f32_e32 v210, v210, v216
	v_add_f32_e32 v211, v211, v217
	ds_bpermute_b32 v214, v185, v208
	ds_bpermute_b32 v215, v185, v209
	ds_bpermute_b32 v216, v185, v210
	ds_bpermute_b32 v217, v185, v211
	s_waitcnt lgkmcnt(0)
	v_add_f32_e32 v208, v208, v214
	v_add_f32_e32 v209, v209, v215
	v_add_f32_e32 v210, v210, v216
	v_add_f32_e32 v211, v211, v217
	v_or_b32_e32 v208, 0x80000000, v208
	v_or_b32_e32 v209, 0x80000000, v209
	v_or_b32_e32 v210, 0x80000000, v210
	v_or_b32_e32 v211, 0x80000000, v211
	s_and_saveexec_b64 s[20:21], s[2:3]
	s_add_u32 s90, s88, 0x4000
	s_addc_u32 s91, s89, 0
	global_store_dword v187, v208, s[90:91] sc0 sc1
	s_add_u32 s90, s88, 0x4800
	s_addc_u32 s91, s89, 0
	global_store_dword v187, v209, s[90:91] sc0 sc1
	s_add_u32 s90, s88, 0x5000
	s_addc_u32 s91, s89, 0
	global_store_dword v187, v210, s[90:91] sc0 sc1
	s_add_u32 s90, s88, 0x5800
	s_addc_u32 s91, s89, 0
	global_store_dword v187, v211, s[90:91] sc0 sc1
	s_or_b64 exec, exec, s[20:21]
	s_barrier
	s_cmp_lg_u32 s59, 0
	s_cbranch_scc1 .Lepi_c1
	s_lshl_b32 s18, s58, 6
	s_add_u32 s18, s18, 0xc020
	s_mov_b64 exec, 1
	v_mov_b32_e32 v175, s18
	v_mov_b32_e32 v255, 1
	global_atomic_add v175, v255, s[50:51]
	s_mov_b64 exec, -1
.Lepi_c1:
	s_waitcnt vmcnt(4)
	v_max3_i32 v214, v188, v189, v190
	v_max3_i32 v214, v214, v191, v192
	v_max3_i32 v214, v214, v193, v194
	v_max3_i32 v214, v214, v195, v196
	v_max3_i32 v214, v214, v197, v198
	v_max3_i32 v214, v214, v199, v200
	v_max3_i32 v214, v214, v201, v202
	v_max3_i32 v214, v214, v203, v104
	v_max3_i32 v214, v214, v105, v106
	v_max3_i32 v214, v214, v107, v108
	v_max3_i32 v214, v214, v109, v110
	v_max3_i32 v214, v214, v111, v112
	v_max3_i32 v214, v214, v113, v114
	v_max3_i32 v214, v214, v115, v120
	v_max3_i32 v214, v214, v121, v122
	v_max_i32_e32 v214, v214, v123
	v_cmp_le_i32_e32 vcc, 0, v214
	s_cbranch_vccnz .Lepi_retry0
.Lepi_ok0:
	v_pk_add_f32 v[188:189], v[188:189], v[190:191]
	v_pk_add_f32 v[192:193], v[192:193], v[194:195]
	v_pk_add_f32 v[188:189], v[188:189], v[192:193]
	v_add_f32_e32 v188, v188, v189
	v_pk_add_f32 v[196:197], v[196:197], v[198:199]
	v_pk_add_f32 v[200:201], v[200:201], v[202:203]
	v_pk_add_f32 v[196:197], v[196:197], v[200:201]
	v_add_f32_e32 v196, v196, v197
	v_pk_add_f32 v[104:105], v[104:105], v[106:107]
	v_pk_add_f32 v[108:109], v[108:109], v[110:111]
	v_pk_add_f32 v[104:105], v[104:105], v[108:109]
	v_add_f32_e32 v104, v104, v105
	v_pk_add_f32 v[112:113], v[112:113], v[114:115]
	v_pk_add_f32 v[120:121], v[120:121], v[122:123]
	v_pk_add_f32 v[112:113], v[112:113], v[120:121]
	v_add_f32_e32 v112, v112, v113
	ds_bpermute_b32 v214, v186, v188
	ds_bpermute_b32 v215, v186, v196
	ds_bpermute_b32 v216, v186, v104
	ds_bpermute_b32 v217, v186, v112
	s_waitcnt lgkmcnt(0)
	v_add_f32_e32 v188, v188, v214
	v_add_f32_e32 v196, v196, v215
	v_add_f32_e32 v104, v104, v216
	v_add_f32_e32 v112, v112, v217
	ds_bpermute_b32 v214, v185, v188
	ds_bpermute_b32 v215, v185, v196
	ds_bpermute_b32 v216, v185, v104
	ds_bpermute_b32 v217, v185, v112
	s_waitcnt lgkmcnt(0)
	v_add_f32_e32 v188, v188, v214
	v_add_f32_e32 v196, v196, v215
	v_add_f32_e32 v104, v104, v216
	v_add_f32_e32 v112, v112, v217
	v_mov_b32_e32 v214, s95
	v_mov_b32_e32 v215, s95
	v_mov_b32_e32 v216, s95
	v_mov_b32_e32 v217, s95
	v_fmac_f32_e32 v214, s94, v188
	v_fmac_f32_e32 v215, s94, v196
	v_fmac_f32_e32 v216, s94, v104
	v_fmac_f32_e32 v217, s94, v112
	v_rsq_f32_e32 v204, v214
	v_rsq_f32_e32 v206, v215
	v_rsq_f32_e32 v208, v216
	v_rsq_f32_e32 v210, v217
	s_nop 1
	s_cmp_lg_u32 s59, 0
	s_cbranch_scc1 .Lepi_d1
	s_waitcnt vmcnt(0)
	s_lshl_b32 s18, s58, 6
	s_add_u32 s18, s18, 0xc020
	s_mov_b64 exec, 1
	v_mov_b32_e32 v175, s18
	s_mov_b32 vcc_lo, 0

; __device__ __forceinline__ void unpack8h(const u32x4 w, f32x4& v0, f32x4& v1) { v0 = (f32x4){h16lo(w.x), h16hi(w.x), h16lo(w.y), h16hi(w.y)}; v1 = (f32x4){h16lo(w.z), h16hi(w.z), h16lo(w.w), h16hi(w.w)}; }
; __device__ __forceinline__ void final_rows(int gw, int lane, const f16* xo, float* out, const float* fg, const float* rowss) {
;     ...
;         for (int rr = 0; rr < 4; ++rr) { part[rr] = lane < 32 ? rowss[(size_t)(r0 + rr) * 32 + lane] : 0.f;
; #pragma unroll
;             for (int j = 0; j < 4; ++j) v[rr][j] = *(const u32x4*)(xo + (size_t)(r0 + rr) * D + 512 * j + 8 * lane); }
;         __builtin_amdgcn_sched_barrier(0);
; #pragma unroll
;         for (int rr = 0; rr < 4; ++rr) { const float rstd = rsqrtf(wave_sum(part[rr]) * (1.f / D) + EPS); float* rp = out + (size_t)(r0 + rr) * D + 8 * lane;
; #pragma unroll
;             for (int j = 0; j < 4; ++j) { f32x4 a0, a1; unpack8h(v[rr][j], a0, a1); *(f32x4*)(rp + 512 * j) = a0 * rstd * g4[j][0]; *(f32x4*)(rp + 512 * j + 4) = a1 * rstd * g4[j][1]; } }
.Lepi_d2:
	s_barrier
	s_add_u32 s90, s26, 0x4000
	s_addc_u32 s91, s27, 0
	global_load_dwordx4 v[234:237], v174, s[90:91]
	global_load_dwordx4 v[238:241], v174, s[90:91] offset:16
	s_add_u32 s90, s26, 0x4800
	s_addc_u32 s91, s27, 0
	global_load_dwordx4 v[242:245], v174, s[90:91]
	global_load_dwordx4 v[246:249], v174, s[90:91] offset:16
	s_add_u32 s90, s26, 0x5000
	s_addc_u32 s91, s27, 0
	global_load_dwordx4 v[218:221], v174, s[90:91]
	global_load_dwordx4 v[222:225], v174, s[90:91] offset:16
	s_add_u32 s90, s26, 0x5800
	s_addc_u32 s91, s27, 0
	global_load_dwordx4 v[226:229], v174, s[90:91]
	global_load_dwordx4 v[230:233], v174, s[90:91] offset:16
	s_cmp_lg_u32 s59, 0
	s_cbranch_scc1 .Lepi_e1
	s_mov_b64 s[86:87], s[82:83]
	v_pk_mul_f32 v[140:141], v[140:141], v[204:205] op_sel_hi:[1,0]
	v_pk_mul_f32 v[142:143], v[142:143], v[204:205] op_sel_hi:[1,0]
	v_pk_mul_f32 v[140:141], v[140:141], v[144:145]
	v_pk_mul_f32 v[142:143], v[142:143], v[146:147]
	v_pk_mul_f32 v[136:137], v[136:137], v[204:205] op_sel_hi:[1,0]
	v_pk_mul_f32 v[138:139], v[138:139], v[204:205] op_sel_hi:[1,0]
	v_pk_mul_f32 v[136:137], v[136:137], v[148:149]
	v_pk_mul_f32 v[138:139], v[138:139], v[150:151]
	v_pk_mul_f32 v[132:133], v[132:133], v[204:205] op_sel_hi:[1,0]
	v_pk_mul_f32 v[134:135], v[134:135], v[204:205] op_sel_hi:[1,0]
	v_pk_mul_f32 v[132:133], v[132:133], v[152:153]
	v_pk_mul_f32 v[134:135], v[134:135], v[154:155]
	v_pk_mul_f32 v[128:129], v[128:129], v[204:205] op_sel_hi:[1,0]
	v_pk_mul_f32 v[130:131], v[130:131], v[204:205] op_sel_hi:[1,0]
	v_pk_mul_f32 v[128:129], v[128:129], v[156:157]
	v_pk_mul_f32 v[130:131], v[130:131], v[158:159]
	global_store_dwordx4 v173, v[140:143], s[86:87]
	global_store_dwordx4 v173, v[136:139], s[86:87] offset:16
	global_store_dwordx4 v173, v[132:135], s[86:87] offset:512
	global_store_dwordx4 v173, v[128:131], s[86:87] offset:528
	s_add_u32 s86, s82, 0x20000
	s_addc_u32 s87, s83, 0
	v_pk_mul_f32 v[124:125], v[124:125], v[206:207] op_sel_hi:[1,0]
	v_pk_mul_f32 v[126:127], v[126:127], v[206:207] op_sel_hi:[1,0]
	v_pk_mul_f32 v[124:125], v[124:125], v[144:145]
	v_pk_mul_f32 v[126:127], v[126:127], v[146:147]
	v_pk_mul_f32 v[116:117], v[116:117], v[206:207] op_sel_hi:[1,0]
	v_pk_mul_f32 v[118:119], v[118:119], v[206:207] op_sel_hi:[1,0]
	v_pk_mul_f32 v[116:117], v[116:117], v[148:149]
	v_pk_mul_f32 v[118:119], v[118:119], v[150:151]
	v_pk_mul_f32 v[100:101], v[100:101], v[206:207] op_sel_hi:[1,0]
	v_pk_mul_f32 v[102:103], v[102:103], v[206:207] op_sel_hi:[1,0]
	v_pk_mul_f32 v[100:101], v[100:101], v[152:153]
	v_pk_mul_f32 v[102:103], v[102:103], v[154:155]
	v_pk_mul_f32 v[96:97], v[96:97], v[206:207] op_sel_hi:[1,0]
	v_pk_mul_f32 v[98:99], v[98:99], v[206:207] op_sel_hi:[1,0]
	v_pk_mul_f32 v[96:97], v[96:97], v[156:157]
	v_pk_mul_f32 v[98:99], v[98:99], v[158:159]
	global_store_dwordx4 v173, v[124:127], s[86:87]
	global_store_dwordx4 v173, v[116:119], s[86:87] offset:16
	global_store_dwordx4 v173, v[100:103], s[86:87] offset:512
	global_store_dwordx4 v173, v[96:99], s[86:87] offset:528
	s_add_u32 s86, s82, 0x40000
	s_addc_u32 s87, s83, 0
	v_pk_mul_f32 v[92:93], v[92:93], v[208:209] op_sel_hi:[1,0]
	v_pk_mul_f32 v[94:95], v[94:95], v[208:209] op_sel_hi:[1,0]
	v_pk_mul_f32 v[92:93], v[92:93], v[144:145]
	v_pk_mul_f32 v[94:95], v[94:95], v[146:147]
	v_pk_mul_f32 v[88:89], v[88:89], v[208:209] op_sel_hi:[1,0]
	v_pk_mul_f32 v[90:91], v[90:91], v[208:209] op_sel_hi:[1,0]
	v_pk_mul_f32 v[88:89], v[88:89], v[148:149]
	v_pk_mul_f32 v[90:91], v[90:91], v[150:151]
	v_pk_mul_f32 v[84:85], v[84:85], v[208:209] op_sel_hi:[1,0]
	v_pk_mul_f32 v[86:87], v[86:87], v[208:209] op_sel_hi:[1,0]
	v_pk_mul_f32 v[84:85], v[84:85], v[152:153]
	v_pk_mul_f32 v[86:87], v[86:87], v[154:155]
	v_pk_mul_f32 v[80:81], v[80:81], v[208:209] op_sel_hi:[1,0]
	v_pk_mul_f32 v[82:83], v[82:83], v[208:209] op_sel_hi:[1,0]
	v_pk_mul_f32 v[80:81], v[80:81], v[156:157]
	v_pk_mul_f32 v[82:83], v[82:83], v[158:159]
	global_store_dwordx4 v173, v[92:95], s[86:87]
	global_store_dwordx4 v173, v[88:91], s[86:87] offset:16
	global_store_dwordx4 v173, v[84:87], s[86:87] offset:512
	global_store_dwordx4 v173, v[80:83], s[86:87] offset:528
	s_add_u32 s86, s82, 0x60000
	s_addc_u32 s87, s83, 0
	v_pk_mul_f32 v[76:77], v[76:77], v[210:211] op_sel_hi:[1,0]
	v_pk_mul_f32 v[78:79], v[78:79], v[210:211] op_sel_hi:[1,0]
	v_pk_mul_f32 v[76:77], v[76:77], v[144:145]
	v_pk_mul_f32 v[78:79], v[78:79], v[146:147]
	v_pk_mul_f32 v[72:73], v[72:73], v[210:211] op_sel_hi:[1,0]
	v_pk_mul_f32 v[74:75], v[74:75], v[210:211] op_sel_hi:[1,0]
	v_pk_mul_f32 v[72:73], v[72:73], v[148:149]
	v_pk_mul_f32 v[74:75], v[74:75], v[150:151]
	v_pk_mul_f32 v[68:69], v[68:69], v[210:211] op_sel_hi:[1,0]
	v_pk_mul_f32 v[70:71], v[70:71], v[210:211] op_sel_hi:[1,0]
	v_pk_mul_f32 v[68:69], v[68:69], v[152:153]
	v_pk_mul_f32 v[70:71], v[70:71], v[154:155]
	v_pk_mul_f32 v[64:65], v[64:65], v[210:211] op_sel_hi:[1,0]
	v_pk_mul_f32 v[66:67], v[66:67], v[210:211] op_sel_hi:[1,0]
	v_pk_mul_f32 v[64:65], v[64:65], v[156:157]
	v_pk_mul_f32 v[66:67], v[66:67], v[158:159]
	global_store_dwordx4 v173, v[76:79], s[86:87]
	global_store_dwordx4 v173, v[72:75], s[86:87] offset:16
	global_store_dwordx4 v173, v[68:71], s[86:87] offset:512
	global_store_dwordx4 v173, v[64:67], s[86:87] offset:528
	s_waitcnt vmcnt(16)
	s_branch .Lepi_e2

; __device__ __forceinline__ void unpack8h(const u32x4 w, f32x4& v0, f32x4& v1) { v0 = (f32x4){h16lo(w.x), h16hi(w.x), h16lo(w.y), h16hi(w.y)}; v1 = (f32x4){h16lo(w.z), h16hi(w.z), h16lo(w.w), h16hi(w.w)}; }
; __device__ __forceinline__ void final_rows(int gw, int lane, const f16* xo, float* out, const float* fg, const float* rowss) {
;     ...
;         for (int rr = 0; rr < 4; ++rr) { part[rr] = lane < 32 ? rowss[(size_t)(r0 + rr) * 32 + lane] : 0.f;
; #pragma unroll
;             for (int j = 0; j < 4; ++j) v[rr][j] = *(const u32x4*)(xo + (size_t)(r0 + rr) * D + 512 * j + 8 * lane); }
;         __builtin_amdgcn_sched_barrier(0);
; #pragma unroll
;         for (int rr = 0; rr < 4; ++rr) { const float rstd = rsqrtf(wave_sum(part[rr]) * (1.f / D) + EPS); float* rp = out + (size_t)(r0 + rr) * D + 8 * lane;
; #pragma unroll
;             for (int j = 0; j < 4; ++j) { f32x4 a0, a1; unpack8h(v[rr][j], a0, a1); *(f32x4*)(rp + 512 * j) = a0 * rstd * g4[j][0]; *(f32x4*)(rp + 512 * j + 4) = a1 * rstd * g4[j][1]; } }
.Lepi_e2:
	v_max3_i32 v214, v234, v235, v236
	v_max3_i32 v214, v214, v237, v238
	v_max3_i32 v214, v214, v239, v240
	v_max3_i32 v214, v214, v241, v242
	v_max3_i32 v214, v214, v243, v244
	v_max3_i32 v214, v214, v245, v246
	v_max3_i32 v214, v214, v247, v248
	v_max3_i32 v214, v214, v249, v218
	v_max3_i32 v214, v214, v219, v220
	v_max3_i32 v214, v214, v221, v222
	v_max3_i32 v214, v214, v223, v224
	v_max3_i32 v214, v214, v225, v226
	v_max3_i32 v214, v214, v227, v228
	v_max3_i32 v214, v214, v229, v230
	v_max3_i32 v214, v214, v231, v232
	v_max_i32_e32 v214, v214, v233
	v_cmp_le_i32_e32 vcc, 0, v214
	s_cbranch_vccnz .Lepi_retry1
.Lepi_ok1:
	v_pk_add_f32 v[234:235], v[234:235], v[236:237]
	v_pk_add_f32 v[238:239], v[238:239], v[240:241]
	v_pk_add_f32 v[234:235], v[234:235], v[238:239]
	v_add_f32_e32 v234, v234, v235
	v_pk_add_f32 v[242:243], v[242:243], v[244:245]
	v_pk_add_f32 v[246:247], v[246:247], v[248:249]
	v_pk_add_f32 v[242:243], v[242:243], v[246:247]
	v_add_f32_e32 v242, v242, v243
	v_pk_add_f32 v[218:219], v[218:219], v[220:221]
	v_pk_add_f32 v[222:223], v[222:223], v[224:225]
	v_pk_add_f32 v[218:219], v[218:219], v[222:223]
	v_add_f32_e32 v218, v218, v219
	v_pk_add_f32 v[226:227], v[226:227], v[228:229]
	v_pk_add_f32 v[230:231], v[230:231], v[232:233]
	v_pk_add_f32 v[226:227], v[226:227], v[230:231]
	v_add_f32_e32 v226, v226, v227
	ds_bpermute_b32 v214, v186, v234
	ds_bpermute_b32 v215, v186, v242
	ds_bpermute_b32 v216, v186, v218
	ds_bpermute_b32 v217, v186, v226
	s_waitcnt lgkmcnt(0)
	v_add_f32_e32 v234, v234, v214
	v_add_f32_e32 v242, v242, v215
	v_add_f32_e32 v218, v218, v216
	v_add_f32_e32 v226, v226, v217
	ds_bpermute_b32 v214, v185, v234
	ds_bpermute_b32 v215, v185, v242
	ds_bpermute_b32 v216, v185, v218
	ds_bpermute_b32 v217, v185, v226
	s_waitcnt lgkmcnt(0)
	v_add_f32_e32 v234, v234, v214
	v_add_f32_e32 v242, v242, v215
	v_add_f32_e32 v218, v218, v216
	v_add_f32_e32 v226, v226, v217
	v_mov_b32_e32 v214, s95
	v_mov_b32_e32 v215, s95
	v_mov_b32_e32 v216, s95
	v_mov_b32_e32 v217, s95
	v_fmac_f32_e32 v214, s94, v234
	v_fmac_f32_e32 v215, s94, v242
	v_fmac_f32_e32 v216, s94, v218
	v_fmac_f32_e32 v217, s94, v226
	v_rsq_f32_e32 v204, v214
	v_rsq_f32_e32 v206, v215
	v_rsq_f32_e32 v208, v216
	v_rsq_f32_e32 v210, v217
	s_nop 1
	s_add_u32 s86, s82, 0x100000
	s_addc_u32 s87, s83, 0
	v_pk_mul_f32 v[60:61], v[60:61], v[204:205] op_sel_hi:[1,0]
	v_pk_mul_f32 v[62:63], v[62:63], v[204:205] op_sel_hi:[1,0]
	v_pk_mul_f32 v[60:61], v[60:61], v[144:145]
	v_pk_mul_f32 v[62:63], v[62:63], v[146:147]
	v_pk_mul_f32 v[56:57], v[56:57], v[204:205] op_sel_hi:[1,0]
	v_pk_mul_f32 v[58:59], v[58:59], v[204:205] op_sel_hi:[1,0]
	v_pk_mul_f32 v[56:57], v[56:57], v[148:149]
	v_pk_mul_f32 v[58:59], v[58:59], v[150:151]
	v_pk_mul_f32 v[52:53], v[52:53], v[204:205] op_sel_hi:[1,0]
	v_pk_mul_f32 v[54:55], v[54:55], v[204:205] op_sel_hi:[1,0]
	v_pk_mul_f32 v[52:53], v[52:53], v[152:153]
	v_pk_mul_f32 v[54:55], v[54:55], v[154:155]
	v_pk_mul_f32 v[48:49], v[48:49], v[204:205] op_sel_hi:[1,0]
	v_pk_mul_f32 v[50:51], v[50:51], v[204:205] op_sel_hi:[1,0]
	v_pk_mul_f32 v[48:49], v[48:49], v[156:157]
	v_pk_mul_f32 v[50:51], v[50:51], v[158:159]
	global_store_dwordx4 v173, v[60:63], s[86:87]
	global_store_dwordx4 v173, v[56:59], s[86:87] offset:16
	global_store_dwordx4 v173, v[52:55], s[86:87] offset:512
	global_store_dwordx4 v173, v[48:51], s[86:87] offset:528
	s_add_u32 s86, s82, 0x120000
	s_addc_u32 s87, s83, 0
	v_pk_mul_f32 v[44:45], v[44:45], v[206:207] op_sel_hi:[1,0]
	v_pk_mul_f32 v[46:47], v[46:47], v[206:207] op_sel_hi:[1,0]
	v_pk_mul_f32 v[44:45], v[44:45], v[144:145]
	v_pk_mul_f32 v[46:47], v[46:47], v[146:147]
	v_pk_mul_f32 v[40:41], v[40:41], v[206:207] op_sel_hi:[1,0]
	v_pk_mul_f32 v[42:43], v[42:43], v[206:207] op_sel_hi:[1,0]
	v_pk_mul_f32 v[40:41], v[40:41], v[148:149]
	v_pk_mul_f32 v[42:43], v[42:43], v[150:151]
	v_pk_mul_f32 v[36:37], v[36:37], v[206:207] op_sel_hi:[1,0]
	v_pk_mul_f32 v[38:39], v[38:39], v[206:207] op_sel_hi:[1,0]
	v_pk_mul_f32 v[36:37], v[36:37], v[152:153]
	v_pk_mul_f32 v[38:39], v[38:39], v[154:155]
	v_pk_mul_f32 v[32:33], v[32:33], v[206:207] op_sel_hi:[1,0]
	v_pk_mul_f32 v[34:35], v[34:35], v[206:207] op_sel_hi:[1,0]
	v_pk_mul_f32 v[32:33], v[32:33], v[156:157]
	v_pk_mul_f32 v[34:35], v[34:35], v[158:159]
	global_store_dwordx4 v173, v[44:47], s[86:87]
	global_store_dwordx4 v173, v[40:43], s[86:87] offset:16
	global_store_dwordx4 v173, v[36:39], s[86:87] offset:512
	global_store_dwordx4 v173, v[32:35], s[86:87] offset:528
	s_add_u32 s86, s82, 0x140000
	s_addc_u32 s87, s83, 0
	v_pk_mul_f32 v[28:29], v[28:29], v[208:209] op_sel_hi:[1,0]
	v_pk_mul_f32 v[30:31], v[30:31], v[208:209] op_sel_hi:[1,0]
	v_pk_mul_f32 v[28:29], v[28:29], v[144:145]
	v_pk_mul_f32 v[30:31], v[30:31], v[146:147]
	v_pk_mul_f32 v[24:25], v[24:25], v[208:209] op_sel_hi:[1,0]
	v_pk_mul_f32 v[26:27], v[26:27], v[208:209] op_sel_hi:[1,0]
	v_pk_mul_f32 v[24:25], v[24:25], v[148:149]
	v_pk_mul_f32 v[26:27], v[26:27], v[150:151]
	v_pk_mul_f32 v[20:21], v[20:21], v[208:209] op_sel_hi:[1,0]
	v_pk_mul_f32 v[22:23], v[22:23], v[208:209] op_sel_hi:[1,0]
	v_pk_mul_f32 v[20:21], v[20:21], v[152:153]
	v_pk_mul_f32 v[22:23], v[22:23], v[154:155]
	v_pk_mul_f32 v[16:17], v[16:17], v[208:209] op_sel_hi:[1,0]
	v_pk_mul_f32 v[18:19], v[18:19], v[208:209] op_sel_hi:[1,0]
	v_pk_mul_f32 v[16:17], v[16:17], v[156:157]
	v_pk_mul_f32 v[18:19], v[18:19], v[158:159]
	global_store_dwordx4 v173, v[28:31], s[86:87]
	global_store_dwordx4 v173, v[24:27], s[86:87] offset:16
	global_store_dwordx4 v173, v[20:23], s[86:87] offset:512
	global_store_dwordx4 v173, v[16:19], s[86:87] offset:528
	s_add_u32 s86, s82, 0x160000
	s_addc_u32 s87, s83, 0
	v_pk_mul_f32 v[12:13], v[12:13], v[210:211] op_sel_hi:[1,0]
	v_pk_mul_f32 v[14:15], v[14:15], v[210:211] op_sel_hi:[1,0]
	v_pk_mul_f32 v[12:13], v[12:13], v[144:145]
	v_pk_mul_f32 v[14:15], v[14:15], v[146:147]
	v_pk_mul_f32 v[8:9], v[8:9], v[210:211] op_sel_hi:[1,0]
	v_pk_mul_f32 v[10:11], v[10:11], v[210:211] op_sel_hi:[1,0]
	v_pk_mul_f32 v[8:9], v[8:9], v[148:149]
	v_pk_mul_f32 v[10:11], v[10:11], v[150:151]
	v_pk_mul_f32 v[4:5], v[4:5], v[210:211] op_sel_hi:[1,0]
	v_pk_mul_f32 v[6:7], v[6:7], v[210:211] op_sel_hi:[1,0]
	v_pk_mul_f32 v[4:5], v[4:5], v[152:153]
	v_pk_mul_f32 v[6:7], v[6:7], v[154:155]
	v_pk_mul_f32 v[0:1], v[0:1], v[210:211] op_sel_hi:[1,0]
	v_pk_mul_f32 v[2:3], v[2:3], v[210:211] op_sel_hi:[1,0]
	v_pk_mul_f32 v[0:1], v[0:1], v[156:157]
	v_pk_mul_f32 v[2:3], v[2:3], v[158:159]
	global_store_dwordx4 v173, v[12:15], s[86:87]
	global_store_dwordx4 v173, v[8:11], s[86:87] offset:16
	global_store_dwordx4 v173, v[4:7], s[86:87] offset:512
	global_store_dwordx4 v173, v[0:3], s[86:87] offset:528
	s_and_b64 vcc, exec, s[4:5]
	s_cbranch_vccz .Lepi_nopre
; __device__ __forceinline__ f32x4 ld_nt(const float* p) { return __builtin_nontemporal_load((const f32x4*)p); }
;     __device__ __forceinline__ void operator()(AccRef acc, const Unit& u, int wr, int wc, int fr, int fq) const {
;     ...
;         const float* gate = mod + (size_t)(u.pm >= 32 ? 1 : 0) * 3 * D + 2 * D + col0;
;         f32x4 gv[2][2];
; #pragma unroll
;         for (int bj = 0; bj < 2; ++bj)
; #pragma unroll
;             for (int n = 0; n < 2; ++n) gv[bj][n] = *(const f32x4*)(gate + bj * HALF + n * 4);
; #pragma unroll
;         for (int ai = 0; ai < 2; ++ai)
; #pragma unroll
;             for (int mp = 0; mp < 2; ++mp) { f32x4 xv[2][2][2];
; #pragma unroll
;                 for (int mm = 0; mm < 2; ++mm)
; #pragma unroll
;                     for (int bj = 0; bj < 2; ++bj)
; #pragma unroll
;                         for (int n = 0; n < 2; ++n) xv[mm][bj][n] = ld_nt(x + (size_t)(row0 + ai * HALF + (mp * 2 + mm) * 16) * D + col0 + bj * HALF + n * 4);
; __device__ __forceinline__ void final_rows(int gw, int lane, const f16* xo, float* out, const float* fg, const float* rowss) {
;     ...
;         for (int rr = 0; rr < 4; ++rr) { part[rr] = lane < 32 ? rowss[(size_t)(r0 + rr) * 32 + lane] : 0.f;
; #pragma unroll
;             for (int j = 0; j < 4; ++j) v[rr][j] = *(const u32x4*)(xo + (size_t)(r0 + rr) * D + 512 * j + 8 * lane); }
;         __builtin_amdgcn_sched_barrier(0);
; #pragma unroll
;         for (int rr = 0; rr < 4; ++rr) { const float rstd = rsqrtf(wave_sum(part[rr]) * (1.f / D) + EPS); float* rp = out + (size_t)(r0 + rr) * D + 8 * lane;
	v_lshl_add_u32 v250, s44, 8, v178
	v_lshl_or_b32 v251, s42, 8, v180
	v_readlane_b32 s98, v254, 2
	v_readlane_b32 s99, v254, 3
	v_lshlrev_b32_e32 v250, 13, v250
	v_lshlrev_b32_e32 v251, 2, v251
	s_cmp_gt_i32 s44, 31
	s_cselect_b32 vcc_lo, 0x6000, 0
	s_add_u32 s100, s50, vcc_lo
	s_addc_u32 s101, s51, 0
	s_add_u32 s100, s100, 0x104000
	s_addc_u32 s101, s101, 0
	v_add_u32_e32 v250, v250, v251
	s_nop 1
	global_load_dwordx4 v[218:221], v251, s[100:101]
	global_load_dwordx4 v[222:225], v251, s[100:101] offset:16
	global_load_dwordx4 v[226:229], v251, s[100:101] offset:512
	global_load_dwordx4 v[230:233], v251, s[100:101] offset:528
	global_load_dwordx4 v[234:237], v250, s[98:99] nt
	global_load_dwordx4 v[238:241], v250, s[98:99] offset:16 nt
	global_load_dwordx4 v[242:245], v250, s[98:99] offset:512 nt
	global_load_dwordx4 v[246:249], v250, s[98:99] offset:528 nt
.Lepi_nopre:
	s_branch .Lepi_done
.Lepi_retry0:
	s_add_u32 s93, s93, 1
	s_cmp_gt_u32 s93, 0x2000
	s_cbranch_scc1 .Lepi_ok0
	s_sleep 1
	s_mov_b64 s[90:91], s[26:27]
	global_load_dwordx4 v[188:191], v174, s[90:91] sc1
	global_load_dwordx4 v[192:195], v174, s[90:91] offset:16 sc1
	s_add_u32 s90, s26, 0x800
	s_addc_u32 s91, s27, 0
	global_load_dwordx4 v[196:199], v174, s[90:91] sc1
	global_load_dwordx4 v[200:203], v174, s[90:91] offset:16 sc1
	s_add_u32 s90, s26, 0x1000
	s_addc_u32 s91, s27, 0
	global_load_dwordx4 v[104:107], v174, s[90:91] sc1
	global_load_dwordx4 v[108:111], v174, s[90:91] offset:16 sc1
	s_add_u32 s90, s26, 0x1800
	s_addc_u32 s91, s27, 0
	global_load_dwordx4 v[112:115], v174, s[90:91] sc1
	global_load_dwordx4 v[120:123], v174, s[90:91] offset:16 sc1
	s_waitcnt vmcnt(0)
	v_max3_i32 v214, v188, v189, v190
	v_max3_i32 v214, v214, v191, v192
	v_max3_i32 v214, v214, v193, v194
	v_max3_i32 v214, v214, v195, v196
	v_max3_i32 v214, v214, v197, v198
	v_max3_i32 v214, v214, v199, v200
	v_max3_i32 v214, v214, v201, v202
	v_max3_i32 v214, v214, v203, v104
	v_max3_i32 v214, v214, v105, v106
	v_max3_i32 v214, v214, v107, v108
	v_max3_i32 v214, v214, v109, v110
	v_max3_i32 v214, v214, v111, v112
	v_max3_i32 v214, v214, v113, v114
	v_max3_i32 v214, v214, v115, v120
	v_max3_i32 v214, v214, v121, v122
	v_max_i32_e32 v214, v214, v123
	v_cmp_le_i32_e32 vcc, 0, v214
	s_cbranch_vccnz .Lepi_retry0
	s_branch .Lepi_ok0
.Lepi_retry1:
	s_add_u32 s93, s93, 1
	s_cmp_gt_u32 s93, 0x2000
	s_cbranch_scc1 .Lepi_ok1
	s_sleep 1
	s_add_u32 s90, s26, 0x4000
	s_addc_u32 s91, s27, 0
	global_load_dwordx4 v[234:237], v174, s[90:91] sc1
	global_load_dwordx4 v[238:241], v174, s[90:91] offset:16 sc1
	s_add_u32 s90, s26, 0x4800
	s_addc_u32 s91, s27, 0
	global_load_dwordx4 v[242:245], v174, s[90:91] sc1
	global_load_dwordx4 v[246:249], v174, s[90:91] offset:16 sc1
	s_add_u32 s90, s26, 0x5000
	s_addc_u32 s91, s27, 0
	global_load_dwordx4 v[218:221], v174, s[90:91] sc1
	global_load_dwordx4 v[222:225], v174, s[90:91] offset:16 sc1
	s_add_u32 s90, s26, 0x5800
	s_addc_u32 s91, s27, 0
	global_load_dwordx4 v[226:229], v174, s[90:91] sc1
	global_load_dwordx4 v[230:233], v174, s[90:91] offset:16 sc1
	s_waitcnt vmcnt(0)
	v_max3_i32 v214, v234, v235, v236
	v_max3_i32 v214, v214, v237, v238
	v_max3_i32 v214, v214, v239, v240
	v_max3_i32 v214, v214, v241, v242
	v_max3_i32 v214, v214, v243, v244
	v_max3_i32 v214, v214, v245, v246
	v_max3_i32 v214, v214, v247, v248
	v_max3_i32 v214, v214, v249, v218
	v_max3_i32 v214, v214, v219, v220
	v_max3_i32 v214, v214, v221, v222
	v_max3_i32 v214, v214, v223, v224
	v_max3_i32 v214, v214, v225, v226
	v_max3_i32 v214, v214, v227, v228
	v_max3_i32 v214, v214, v229, v230
	v_max3_i32 v214, v214, v231, v232
	v_max_i32_e32 v214, v214, v233
	v_cmp_le_i32_e32 vcc, 0, v214
	s_cbranch_vccnz .Lepi_retry1
	s_branch .Lepi_ok1
